# cache policy: non-temporal (nt) loads for the once-read out stream in the final-norm phase
# speedup vs baseline: 1.0037x; 1.0037x over previous
; __device__ __forceinline__ void p14_final(const Ctx& C) {
;     ...
;     for (int row0 = gw * 4; row0 < MT; row0 += NGW * 4) {
;         f32x4 v[4][4]; float rs[4];
; #pragma unroll
;         for (int q = 0; q < 4; ++q) { rs[q] = __builtin_amdgcn_rsqf(ss3[row0 + q] * (1.f / 1024.f) + EPS);
; #pragma unroll
;             for (int j = 0; j < 4; ++j) v[q][j] = *(const f32x4*)(C.out + O_Y + (size_t)(row0 + q) * DM + 256 * j + 4 * C.lane); }
; #pragma unroll
;         for (int q = 0; q < 4; ++q)
; #pragma unroll
;             for (int j = 0; j < 4; ++j) { const int c = 256 * j + 4 * C.lane; __builtin_nontemporal_store(v[q][j] * rs[q] * *(const f32x4*)(gf + c), (f32x4*)(C.out + O_Y + (size_t)(row0 + q) * DM + c)); } }
.LBB0_1730:
	global_load_dwordx4 v[2:5], v141, s[4:5] offset:-12
	v_add_co_u32_e32 v24, vcc, 0xffffd000, v8
	s_add_i32 s0, s0, s2
	s_nop 0
	v_addc_co_u32_e32 v25, vcc, -1, v9, vcc
	global_load_dwordx4 v[12:15], v[24:25], off offset:-3072 nt
	global_load_dwordx4 v[16:19], v[6:7], off nt
	global_load_dwordx4 v[20:23], v[24:25], off offset:-2048 nt
	v_add_co_u32_e32 v26, vcc, 0xffffe000, v8
	s_add_u32 s4, s4, s6
	s_nop 0
	v_addc_co_u32_e32 v27, vcc, -1, v9, vcc
	s_addc_u32 s5, s5, s7
	s_cmp_lt_i32 s0, 0x8200
	s_waitcnt vmcnt(3)
	v_fmamk_f32 v2, v2, 0x3a800000, v10
	v_rsq_f32_e32 v2, v2
	s_waitcnt vmcnt(2)
	v_pk_mul_f32 v[14:15], v[14:15], v[2:3] op_sel_hi:[1,0]
	v_pk_mul_f32 v[12:13], v[12:13], v[2:3] op_sel_hi:[1,0]
	s_waitcnt vmcnt(1)
	v_pk_mul_f32 v[14:15], v[14:15], v[18:19]
	v_pk_mul_f32 v[12:13], v[12:13], v[16:17]
	global_store_dwordx4 v[24:25], v[12:15], off offset:-3072 nt
	global_load_dwordx4 v[12:15], v[6:7], off offset:1024 nt
	s_nop 0
	global_load_dwordx4 v[16:19], v[24:25], off offset:-1024 nt
	s_waitcnt vmcnt(3)
	v_pk_mul_f32 v[22:23], v[22:23], v[2:3] op_sel_hi:[1,0]
	v_pk_mul_f32 v[20:21], v[20:21], v[2:3] op_sel_hi:[1,0]
	s_waitcnt vmcnt(1)
	v_pk_mul_f32 v[14:15], v[22:23], v[14:15]
	v_pk_mul_f32 v[12:13], v[20:21], v[12:13]
	global_store_dwordx4 v[24:25], v[12:15], off offset:-2048 nt
	global_load_dwordx4 v[12:15], v[6:7], off offset:2048 nt
	s_nop 0
	global_load_dwordx4 v[20:23], v[24:25], off nt
	s_waitcnt vmcnt(3)
	v_pk_mul_f32 v[18:19], v[18:19], v[2:3] op_sel_hi:[1,0]
	v_pk_mul_f32 v[16:17], v[16:17], v[2:3] op_sel_hi:[1,0]
	s_waitcnt vmcnt(1)
	v_pk_mul_f32 v[14:15], v[18:19], v[14:15]
	v_pk_mul_f32 v[12:13], v[16:17], v[12:13]
	global_store_dwordx4 v[24:25], v[12:15], off offset:-1024 nt
	global_load_dwordx4 v[12:15], v[6:7], off offset:3072 nt
	s_waitcnt vmcnt(2)
	v_pk_mul_f32 v[22:23], v[22:23], v[2:3] op_sel_hi:[1,0]
	v_pk_mul_f32 v[20:21], v[20:21], v[2:3] op_sel_hi:[1,0]
	global_load_dwordx4 v[16:19], v[26:27], off offset:-3072 nt
	v_fmamk_f32 v2, v3, 0x3a800000, v10
	v_rsq_f32_e32 v2, v2
	s_waitcnt vmcnt(1)
	v_pk_mul_f32 v[14:15], v[22:23], v[14:15]
	v_pk_mul_f32 v[12:13], v[20:21], v[12:13]
	global_store_dwordx4 v[24:25], v[12:15], off nt
	global_load_dwordx4 v[12:15], v[6:7], off nt
	s_nop 0
	global_load_dwordx4 v[20:23], v[26:27], off offset:-2048 nt
	s_waitcnt vmcnt(3)
	v_pk_mul_f32 v[18:19], v[18:19], v[2:3] op_sel_hi:[1,0]
	v_pk_mul_f32 v[16:17], v[16:17], v[2:3] op_sel_hi:[1,0]
	v_add_co_u32_e32 v24, vcc, 0xfffff000, v8
	s_waitcnt vmcnt(1)
	v_pk_mul_f32 v[14:15], v[18:19], v[14:15]
	v_pk_mul_f32 v[12:13], v[16:17], v[12:13]
	global_store_dwordx4 v[26:27], v[12:15], off offset:-3072 nt
	global_load_dwordx4 v[12:15], v[6:7], off offset:1024 nt
	s_nop 0
	global_load_dwordx4 v[16:19], v[26:27], off offset:-1024 nt
	s_waitcnt vmcnt(3)
	v_pk_mul_f32 v[22:23], v[22:23], v[2:3] op_sel_hi:[1,0]
	v_pk_mul_f32 v[20:21], v[20:21], v[2:3] op_sel_hi:[1,0]
	v_addc_co_u32_e32 v25, vcc, -1, v9, vcc
	s_waitcnt vmcnt(1)
	v_pk_mul_f32 v[14:15], v[22:23], v[14:15]
	v_pk_mul_f32 v[12:13], v[20:21], v[12:13]
	global_store_dwordx4 v[26:27], v[12:15], off offset:-2048 nt
	global_load_dwordx4 v[12:15], v[6:7], off offset:2048 nt
	s_nop 0
	global_load_dwordx4 v[20:23], v[26:27], off nt
	s_waitcnt vmcnt(3)
	v_pk_mul_f32 v[18:19], v[18:19], v[2:3] op_sel_hi:[1,0]
	v_pk_mul_f32 v[16:17], v[16:17], v[2:3] op_sel_hi:[1,0]
	s_waitcnt vmcnt(1)
	v_pk_mul_f32 v[14:15], v[18:19], v[14:15]
	v_pk_mul_f32 v[12:13], v[16:17], v[12:13]
	global_store_dwordx4 v[26:27], v[12:15], off offset:-1024 nt
	global_load_dwordx4 v[12:15], v[6:7], off offset:3072 nt
	s_waitcnt vmcnt(2)
; __device__ __forceinline__ void p14_final(const Ctx& C) {
;     ...
;     for (int row0 = gw * 4; row0 < MT; row0 += NGW * 4) {
;         f32x4 v[4][4]; float rs[4];
; #pragma unroll
;         for (int q = 0; q < 4; ++q) { rs[q] = __builtin_amdgcn_rsqf(ss3[row0 + q] * (1.f / 1024.f) + EPS);
; #pragma unroll
;             for (int j = 0; j < 4; ++j) v[q][j] = *(const f32x4*)(C.out + O_Y + (size_t)(row0 + q) * DM + 256 * j + 4 * C.lane); }
; #pragma unroll
;         for (int q = 0; q < 4; ++q)
; #pragma unroll
;             for (int j = 0; j < 4; ++j) { const int c = 256 * j + 4 * C.lane; __builtin_nontemporal_store(v[q][j] * rs[q] * *(const f32x4*)(gf + c), (f32x4*)(C.out + O_Y + (size_t)(row0 + q) * DM + c)); } }
	v_pk_mul_f32 v[22:23], v[22:23], v[2:3] op_sel_hi:[1,0]
	v_pk_mul_f32 v[2:3], v[20:21], v[2:3] op_sel_hi:[1,0]
	global_load_dwordx4 v[16:19], v[24:25], off offset:-3072 nt
	s_waitcnt vmcnt(1)
	v_pk_mul_f32 v[14:15], v[22:23], v[14:15]
	v_pk_mul_f32 v[12:13], v[2:3], v[12:13]
	global_store_dwordx4 v[26:27], v[12:15], off nt
	global_load_dwordx4 v[12:15], v[6:7], off nt
	s_nop 0
	global_load_dwordx4 v[20:23], v[24:25], off offset:-2048 nt
	v_fmamk_f32 v2, v4, 0x3a800000, v10
	v_rsq_f32_e32 v2, v2
	s_waitcnt vmcnt(3)
	v_pk_mul_f32 v[18:19], v[18:19], v[2:3] op_sel_hi:[1,0]
	v_pk_mul_f32 v[16:17], v[16:17], v[2:3] op_sel_hi:[1,0]
	s_waitcnt vmcnt(1)
	v_pk_mul_f32 v[14:15], v[18:19], v[14:15]
	v_pk_mul_f32 v[12:13], v[16:17], v[12:13]
	global_store_dwordx4 v[24:25], v[12:15], off offset:-3072 nt
	global_load_dwordx4 v[12:15], v[6:7], off offset:1024 nt
	s_nop 0
	global_load_dwordx4 v[16:19], v[24:25], off offset:-1024 nt
	s_waitcnt vmcnt(3)
	v_pk_mul_f32 v[22:23], v[22:23], v[2:3] op_sel_hi:[1,0]
	v_pk_mul_f32 v[20:21], v[20:21], v[2:3] op_sel_hi:[1,0]
	s_waitcnt vmcnt(1)
	v_pk_mul_f32 v[14:15], v[22:23], v[14:15]
	v_pk_mul_f32 v[12:13], v[20:21], v[12:13]
	global_store_dwordx4 v[24:25], v[12:15], off offset:-2048 nt
	global_load_dwordx4 v[12:15], v[6:7], off offset:2048 nt
	s_nop 0
	global_load_dwordx4 v[20:23], v[8:9], off offset:-4096 nt
	s_waitcnt vmcnt(3)
	v_pk_mul_f32 v[18:19], v[18:19], v[2:3] op_sel_hi:[1,0]
	v_pk_mul_f32 v[16:17], v[16:17], v[2:3] op_sel_hi:[1,0]
	s_waitcnt vmcnt(1)
	v_pk_mul_f32 v[14:15], v[18:19], v[14:15]
	v_pk_mul_f32 v[12:13], v[16:17], v[12:13]
	global_store_dwordx4 v[24:25], v[12:15], off offset:-1024 nt
	global_load_dwordx4 v[12:15], v[6:7], off offset:3072 nt
	s_nop 0
	global_load_dwordx4 v[16:19], v[8:9], off offset:-3072 nt
	s_waitcnt vmcnt(3)
	v_pk_mul_f32 v[22:23], v[22:23], v[2:3] op_sel_hi:[1,0]
	v_pk_mul_f32 v[2:3], v[20:21], v[2:3] op_sel_hi:[1,0]
	s_waitcnt vmcnt(1)
	v_pk_mul_f32 v[14:15], v[22:23], v[14:15]
	v_pk_mul_f32 v[12:13], v[2:3], v[12:13]
	global_store_dwordx4 v[8:9], v[12:15], off offset:-4096 nt
	global_load_dwordx4 v[12:15], v[6:7], off nt
	s_nop 0
	global_load_dwordx4 v[20:23], v[8:9], off offset:-2048 nt
	v_fmamk_f32 v2, v5, 0x3a800000, v10
	v_rsq_f32_e32 v24, v2
	s_waitcnt vmcnt(3)
	v_pk_mul_f32 v[2:3], v[18:19], v[24:25] op_sel_hi:[1,0]
	v_pk_mul_f32 v[16:17], v[16:17], v[24:25] op_sel_hi:[1,0]
	s_waitcnt vmcnt(1)
	v_pk_mul_f32 v[4:5], v[2:3], v[14:15]
	v_pk_mul_f32 v[2:3], v[16:17], v[12:13]
	global_store_dwordx4 v[8:9], v[2:5], off offset:-3072 nt
	global_load_dwordx4 v[2:5], v[6:7], off offset:1024 nt
	s_nop 0
	global_load_dwordx4 v[12:15], v[8:9], off offset:-1024 nt
	s_waitcnt vmcnt(3)
	v_pk_mul_f32 v[16:17], v[22:23], v[24:25] op_sel_hi:[1,0]
	v_pk_mul_f32 v[18:19], v[20:21], v[24:25] op_sel_hi:[1,0]
	s_waitcnt vmcnt(1)
	v_pk_mul_f32 v[4:5], v[16:17], v[4:5]
	v_pk_mul_f32 v[2:3], v[18:19], v[2:3]
	global_store_dwordx4 v[8:9], v[2:5], off offset:-2048 nt
	global_load_dwordx4 v[2:5], v[6:7], off offset:2048 nt
	s_nop 0
	global_load_dwordx4 v[16:19], v[8:9], off nt
	s_waitcnt vmcnt(3)
	v_pk_mul_f32 v[14:15], v[14:15], v[24:25] op_sel_hi:[1,0]
	v_pk_mul_f32 v[12:13], v[12:13], v[24:25] op_sel_hi:[1,0]
	s_waitcnt vmcnt(1)
	v_pk_mul_f32 v[4:5], v[14:15], v[4:5]
	v_pk_mul_f32 v[2:3], v[12:13], v[2:3]
	global_store_dwordx4 v[8:9], v[2:5], off offset:-1024 nt
	global_load_dwordx4 v[2:5], v[6:7], off offset:3072 nt
	s_waitcnt vmcnt(2)
	v_pk_mul_f32 v[12:13], v[18:19], v[24:25] op_sel_hi:[1,0]
	v_pk_mul_f32 v[14:15], v[16:17], v[24:25] op_sel_hi:[1,0]
	s_waitcnt vmcnt(0)
	v_pk_mul_f32 v[4:5], v[12:13], v[4:5]
	v_pk_mul_f32 v[2:3], v[14:15], v[2:3]
	global_store_dwordx4 v[8:9], v[2:5], off nt
	v_lshl_add_u64 v[8:9], v[8:9], 0, s[8:9]
	s_cbranch_scc1 .LBB0_1730
